# speedup vs baseline: 1.0015x; 1.0015x over previous
; __device__ __forceinline__ unsigned cvt_pk_bf16(float lo, float hi) { f32x2_t v = {lo, hi}; bf16x2_t b = __builtin_convertvector(v, bf16x2_t); return __builtin_bit_cast(unsigned, b); }
; template <bool HB, bool FINAL>
; __device__ __forceinline__ void norm_rows(const void* src, const bf16* y, float ys, bf16* hdst, const float* gain, bf16* xn, float* fout, float* fstage, int gw, int NGW, int lane) {
;     ...
;         for (int r = 0; r < 2; ++r) { const int m = m0 + r * NGW; const float rstd = rsqrtf(s[r] * (1.f / D) + EPS);
;             if (!FINAL && hdst) { u32x2* hr = (u32x2*)(hdst + (size_t)m * D) + lane;
; #pragma unroll
;                 for (int j = 0; j < 4; ++j) { u32x2 w; w.x = cvt_pk_bf16(v[r][j].x, v[r][j].y); w.y = cvt_pk_bf16(v[r][j].z, v[r][j].w); hr[64 * j] = w; } }
;             if (FINAL) { f32x4* o = (f32x4*)((m >= T / 2 ? fout : fstage) + (size_t)m * D) + lane;
; #pragma unroll
;                 for (int j = 0; j < 4; ++j) o[64 * j] = v[r][j] * rstd * gv[j];
;             } else { u32x2* o = (u32x2*)(xn + (size_t)m * D) + lane;
; #pragma unroll
;                 for (int j = 0; j < 4; ++j) { const f32x4 q = v[r][j] * rstd * gv[j]; u32x2 w; w.x = cvt_pk_bf16(q.x, q.y); w.y = cvt_pk_bf16(q.z, q.w); o[64 * j] = w; } } }
.LBB0_254:
	s_waitcnt lgkmcnt(0)
	v_add_f32_e32 v26, v48, v49
	v_fmamk_f32 v26, v26, 0x3a800000, v142
	v_mul_f32_e32 v27, 0x4b800000, v26
	v_cmp_gt_f32_e32 vcc, s72, v26
	s_add_i32 s6, s12, s33
	s_cmpk_gt_i32 s6, 0x7fff
	v_cndmask_b32_e32 v26, v26, v27, vcc
	v_rsq_f32_e32 v28, v26
	v_lshl_add_u64 v[26:27], v[22:23], 0, s[14:15]
	v_mul_f32_e32 v29, 0x45800000, v28
	v_cndmask_b32_e32 v28, v28, v29, vcc
	v_pk_mul_f32 v[30:31], v[60:61], v[28:29] op_sel_hi:[1,0]
	v_pk_mul_f32 v[32:33], v[54:55], v[28:29] op_sel_hi:[1,0]
	v_pk_mul_f32 v[30:31], v[2:3], v[30:31]
	v_pk_mul_f32 v[32:33], v[4:5], v[32:33]
	v_cvt_pk_bf16_f32 v30, v30, v31
	v_cvt_pk_bf16_f32 v31, v32, v33
	global_store_dwordx2 v[26:27], v[30:31], off sc1
	v_pk_mul_f32 v[30:31], v[58:59], v[28:29] op_sel_hi:[1,0]
	v_pk_mul_f32 v[32:33], v[50:51], v[28:29] op_sel_hi:[1,0]
	v_pk_mul_f32 v[30:31], v[6:7], v[30:31]
	v_pk_mul_f32 v[32:33], v[8:9], v[32:33]
	v_cvt_pk_bf16_f32 v30, v30, v31
	v_cvt_pk_bf16_f32 v31, v32, v33
	global_store_dwordx2 v[26:27], v[30:31], off offset:512 sc1
	v_pk_mul_f32 v[30:31], v[56:57], v[28:29] op_sel_hi:[1,0]
	v_pk_mul_f32 v[32:33], v[46:47], v[28:29] op_sel_hi:[1,0]
	v_pk_mul_f32 v[30:31], v[10:11], v[30:31]
	v_pk_mul_f32 v[32:33], v[12:13], v[32:33]
	v_cvt_pk_bf16_f32 v30, v30, v31
	v_cvt_pk_bf16_f32 v31, v32, v33
	global_store_dwordx2 v[26:27], v[30:31], off offset:1024 sc1
	v_pk_mul_f32 v[30:31], v[52:53], v[28:29] op_sel_hi:[1,0]
	v_pk_mul_f32 v[28:29], v[44:45], v[28:29] op_sel_hi:[1,0]
	v_pk_mul_f32 v[30:31], v[14:15], v[30:31]
	v_pk_mul_f32 v[28:29], v[16:17], v[28:29]
	v_cvt_pk_bf16_f32 v30, v30, v31
	v_cvt_pk_bf16_f32 v31, v28, v29
	global_store_dwordx2 v[26:27], v[30:31], off offset:1536 sc1
	s_cbranch_scc1 .LBB0_259
	s_cmp_lg_u64 s[10:11], 0
	s_cbranch_scc1 .LN_w16
	s_waitcnt vmcnt(8)
	s_branch .LN_copy

; __device__ __forceinline__ unsigned cvt_pk_bf16(float lo, float hi) { f32x2_t v = {lo, hi}; bf16x2_t b = __builtin_convertvector(v, bf16x2_t); return __builtin_bit_cast(unsigned, b); }
; template <bool HB, bool FINAL>
; __device__ __forceinline__ void norm_rows(const void* src, const bf16* y, float ys, bf16* hdst, const float* gain, bf16* xn, float* fout, float* fstage, int gw, int NGW, int lane) {
;     ...
;             if (HB) { const u32x2* hr = (const u32x2*)((const bf16*)src + (size_t)m * D) + lane;
; #pragma unroll
;                 for (int j = 0; j < 4; ++j) { const u32x2 w = hr[64 * j]; v[r][j] = (f32x4){__uint_as_float(w.x << 16), __uint_as_float(w.x & 0xffff0000u), __uint_as_float(w.y << 16), __uint_as_float(w.y & 0xffff0000u)}; }
;             } else { const f32x4* xr = (const f32x4*)((const float*)src + (size_t)m * D) + lane;
; #pragma unroll
;                 for (int j = 0; j < 4; ++j) v[r][j] = xr[64 * j]; }
;             if (y) { const u32x2* yr = (const u32x2*)(y + (size_t)m * D) + lane;
; #pragma unroll
;                 for (int j = 0; j < 4; ++j) yw[r][j] = yr[64 * j]; } }
;         float s[2];
; #pragma unroll
;         for (int r = 0; r < 2; ++r) { s[r] = 0.f;
;             if (y) {
; #pragma unroll
;                 for (int j = 0; j < 4; ++j) { const u32x2 w = yw[r][j];
;                     v[r][j].x += ys * __uint_as_float(w.x << 16); v[r][j].y += ys * __uint_as_float(w.x & 0xffff0000u); v[r][j].z += ys * __uint_as_float(w.y << 16); v[r][j].w += ys * __uint_as_float(w.y & 0xffff0000u); } }
; #pragma unroll
;             for (int j = 0; j < 4; ++j) s[r] += (v[r][j].x * v[r][j].x + v[r][j].y * v[r][j].y) + (v[r][j].z * v[r][j].z + v[r][j].w * v[r][j].w); }
; #pragma unroll
;         for (int o = 1; o < 64; o <<= 1) { s[0] += __shfl_xor(s[0], o); s[1] += __shfl_xor(s[1], o); }
; #pragma unroll
;         for (int r = 0; r < 2; ++r) { const int m = m0 + r * NGW; const float rstd = rsqrtf(s[r] * (1.f / D) + EPS);
;             if (!FINAL && hdst) { u32x2* hr = (u32x2*)(hdst + (size_t)m * D) + lane;
; #pragma unroll
;                 for (int j = 0; j < 4; ++j) { u32x2 w; w.x = cvt_pk_bf16(v[r][j].x, v[r][j].y); w.y = cvt_pk_bf16(v[r][j].z, v[r][j].w); hr[64 * j] = w; } }
.LN_C:
	s_andn2_b64 vcc, exec, s[10:11]
	v_lshlrev_b32_e32 v26, 16, v28
	v_and_b32_e32 v27, 0xffff0000, v28
	v_lshlrev_b32_e32 v70, 16, v30
	v_and_b32_e32 v71, 0xffff0000, v30
	v_lshlrev_b32_e32 v28, 16, v29
	v_and_b32_e32 v29, 0xffff0000, v29
	v_lshlrev_b32_e32 v30, 16, v31
	v_and_b32_e32 v31, 0xffff0000, v31
	v_pk_fma_f32 v[26:27], v[34:35], v[70:71], v[26:27]
	v_pk_fma_f32 v[28:29], v[34:35], v[30:31], v[28:29]
	v_lshlrev_b32_e32 v30, 16, v32
	v_and_b32_e32 v31, 0xffff0000, v32
	v_lshlrev_b32_e32 v70, 16, v36
	v_and_b32_e32 v71, 0xffff0000, v36
	v_lshlrev_b32_e32 v32, 16, v33
	v_and_b32_e32 v33, 0xffff0000, v33
	v_lshlrev_b32_e32 v36, 16, v37
	v_and_b32_e32 v37, 0xffff0000, v37
	v_pk_fma_f32 v[30:31], v[34:35], v[70:71], v[30:31]
	v_pk_fma_f32 v[32:33], v[34:35], v[36:37], v[32:33]
	v_lshlrev_b32_e32 v36, 16, v38
	v_and_b32_e32 v37, 0xffff0000, v38
	v_lshlrev_b32_e32 v70, 16, v40
	v_and_b32_e32 v71, 0xffff0000, v40
	v_lshlrev_b32_e32 v38, 16, v39
	v_and_b32_e32 v39, 0xffff0000, v39
	v_lshlrev_b32_e32 v40, 16, v41
	v_and_b32_e32 v41, 0xffff0000, v41
	v_pk_fma_f32 v[36:37], v[34:35], v[70:71], v[36:37]
	v_pk_fma_f32 v[38:39], v[34:35], v[40:41], v[38:39]
	v_lshlrev_b32_e32 v40, 16, v42
	v_and_b32_e32 v41, 0xffff0000, v42
	v_lshlrev_b32_e32 v70, 16, v60
	v_and_b32_e32 v71, 0xffff0000, v60
	v_pk_fma_f32 v[40:41], v[34:35], v[70:71], v[40:41]
	v_lshlrev_b32_e32 v42, 16, v43
	v_and_b32_e32 v43, 0xffff0000, v43
	v_lshlrev_b32_e32 v60, 16, v61
	v_and_b32_e32 v61, 0xffff0000, v61
	v_mov_b32_e32 v70, v27
	v_mov_b32_e32 v71, v29
	v_pk_fma_f32 v[42:43], v[34:35], v[60:61], v[42:43]
	v_mov_b32_e32 v60, v26
	v_mov_b32_e32 v61, v28
	v_pk_mul_f32 v[70:71], v[70:71], v[70:71]
	v_mov_b32_e32 v72, v31
	v_mov_b32_e32 v73, v33
	v_pk_fma_f32 v[60:61], v[60:61], v[60:61], v[70:71]
	v_mov_b32_e32 v70, v30
	v_mov_b32_e32 v71, v32
	v_pk_mul_f32 v[72:73], v[72:73], v[72:73]
	v_mul_f32_e32 v74, v39, v39
	v_pk_fma_f32 v[70:71], v[70:71], v[70:71], v[72:73]
	v_mul_f32_e32 v72, v37, v37
	v_pk_add_f32 v[60:61], v[60:61], v[60:61] op_sel:[0,1] op_sel_hi:[1,0]
	v_pk_add_f32 v[70:71], v[70:71], v[70:71] op_sel:[0,1] op_sel_hi:[1,0]
	v_pk_fma_f32 v[72:73], v[36:37], v[36:37], v[72:73] op_sel_hi:[1,1,0]
	v_pk_fma_f32 v[74:75], v[38:39], v[38:39], v[74:75] op_sel_hi:[1,1,0]
	v_pk_mul_f32 v[76:77], v[40:41], v[40:41]
	v_pk_mul_f32 v[78:79], v[42:43], v[42:43]
	v_mov_b32_e32 v61, v76
	v_mov_b32_e32 v71, v77
	v_mov_b32_e32 v73, v78
	v_mov_b32_e32 v75, v79
	v_pk_add_f32 v[60:61], v[60:61], v[70:71]
	v_pk_add_f32 v[70:71], v[72:73], v[74:75]
	s_nop 0
	v_pk_add_f32 v[60:61], v[60:61], v[70:71]
	v_lshlrev_b32_e32 v70, 16, v58
	v_add_f32_e32 v69, v60, v61
	v_lshlrev_b32_e32 v60, 16, v54
	v_and_b32_e32 v61, 0xffff0000, v54
	v_and_b32_e32 v71, 0xffff0000, v58
	v_lshlrev_b32_e32 v54, 16, v55
	v_and_b32_e32 v55, 0xffff0000, v55
	v_lshlrev_b32_e32 v58, 16, v59
	v_and_b32_e32 v59, 0xffff0000, v59
	v_pk_fma_f32 v[60:61], v[34:35], v[70:71], v[60:61]
	v_pk_fma_f32 v[54:55], v[34:35], v[58:59], v[54:55]
	v_lshlrev_b32_e32 v58, 16, v50
	v_and_b32_e32 v59, 0xffff0000, v50
	v_lshlrev_b32_e32 v70, 16, v56
	v_and_b32_e32 v71, 0xffff0000, v56
	v_lshlrev_b32_e32 v50, 16, v51
	v_and_b32_e32 v51, 0xffff0000, v51
	v_lshlrev_b32_e32 v56, 16, v57
	v_and_b32_e32 v57, 0xffff0000, v57
	v_pk_fma_f32 v[58:59], v[34:35], v[70:71], v[58:59]
	v_pk_fma_f32 v[50:51], v[34:35], v[56:57], v[50:51]
	v_lshlrev_b32_e32 v56, 16, v46
	v_and_b32_e32 v57, 0xffff0000, v46
	v_lshlrev_b32_e32 v70, 16, v52
	v_and_b32_e32 v71, 0xffff0000, v52
	v_lshlrev_b32_e32 v46, 16, v47
	v_and_b32_e32 v47, 0xffff0000, v47
	v_lshlrev_b32_e32 v52, 16, v53
	v_and_b32_e32 v53, 0xffff0000, v53
	v_pk_fma_f32 v[56:57], v[34:35], v[70:71], v[56:57]
	v_pk_fma_f32 v[46:47], v[34:35], v[52:53], v[46:47]
	v_lshlrev_b32_e32 v52, 16, v44
	v_and_b32_e32 v53, 0xffff0000, v44
	v_lshlrev_b32_e32 v70, 16, v48
	v_and_b32_e32 v71, 0xffff0000, v48
	v_lshlrev_b32_e32 v44, 16, v45
	v_and_b32_e32 v45, 0xffff0000, v45
	v_lshlrev_b32_e32 v48, 16, v49
	v_and_b32_e32 v49, 0xffff0000, v49
	v_pk_fma_f32 v[52:53], v[34:35], v[70:71], v[52:53]
	v_pk_fma_f32 v[44:45], v[34:35], v[48:49], v[44:45]
	v_pk_mul_f32 v[48:49], v[60:61], v[60:61]
	v_pk_mul_f32 v[70:71], v[54:55], v[54:55]
	v_pk_mul_f32 v[72:73], v[58:59], v[58:59]
	v_pk_mul_f32 v[74:75], v[50:51], v[50:51]
	v_pk_mul_f32 v[76:77], v[56:57], v[56:57]
	v_pk_mul_f32 v[78:79], v[46:47], v[46:47]
	v_add_f32_e32 v74, v74, v75
	v_add_f32_e32 v72, v72, v73
	v_add_f32_e32 v70, v70, v71
	v_add_f32_e32 v48, v48, v49
	v_add_f32_e32 v72, v72, v74
	v_add_f32_e32 v48, v48, v70
	v_add_f32_e32 v49, v78, v79
	v_add_f32_e32 v70, v76, v77
	v_pk_mul_f32 v[80:81], v[52:53], v[52:53]
	v_pk_mul_f32 v[82:83], v[44:45], v[44:45]
	v_add_f32_e32 v48, v48, v72
	v_add_f32_e32 v49, v70, v49
	v_add_f32_e32 v48, v48, v49
	v_add_f32_e32 v49, v82, v83
	v_add_f32_e32 v70, v80, v81
	v_add_f32_e32 v49, v70, v49
	v_add_f32_e32 v48, v48, v49
	ds_bpermute_b32 v49, v62, v69
	v_cndmask_b32_e64 v71, 0, 1, s[10:11]
	v_cmp_ne_u32_e64 s[6:7], 1, v71
	s_waitcnt lgkmcnt(0)
	v_add_f32_e32 v49, v69, v49
	ds_bpermute_b32 v69, v62, v48
	s_waitcnt lgkmcnt(0)
	v_add_f32_e32 v48, v48, v69
	ds_bpermute_b32 v69, v63, v49
	s_waitcnt lgkmcnt(0)
	v_add_f32_e32 v49, v49, v69
	ds_bpermute_b32 v69, v63, v48
	s_waitcnt lgkmcnt(0)
	v_add_f32_e32 v48, v48, v69
	ds_bpermute_b32 v69, v64, v49
	s_waitcnt lgkmcnt(0)
	v_add_f32_e32 v49, v49, v69
	ds_bpermute_b32 v69, v64, v48
	s_waitcnt lgkmcnt(0)
	v_add_f32_e32 v48, v48, v69
	ds_bpermute_b32 v69, v65, v49
	s_waitcnt lgkmcnt(0)
	v_add_f32_e32 v49, v49, v69
	ds_bpermute_b32 v69, v65, v48
	s_waitcnt lgkmcnt(0)
	v_add_f32_e32 v48, v48, v69
	ds_bpermute_b32 v69, v66, v49
	s_waitcnt lgkmcnt(0)
	v_add_f32_e32 v69, v49, v69
	ds_bpermute_b32 v49, v66, v48
	ds_bpermute_b32 v70, v67, v69
	s_waitcnt lgkmcnt(1)
	v_add_f32_e32 v48, v48, v49
	ds_bpermute_b32 v49, v67, v48
	s_cbranch_vccnz .LBB0_257
	v_lshl_add_u64 v[72:73], v[24:25], 0, s[16:17]
	v_cvt_pk_bf16_f32 v74, v26, v27
	v_cvt_pk_bf16_f32 v75, v28, v29
	global_store_dwordx2 v[72:73], v[74:75], off sc1
	v_cvt_pk_bf16_f32 v74, v30, v31
	v_cvt_pk_bf16_f32 v75, v32, v33
	global_store_dwordx2 v[72:73], v[74:75], off offset:512 sc1
	v_cvt_pk_bf16_f32 v74, v36, v37
	v_cvt_pk_bf16_f32 v75, v38, v39
	global_store_dwordx2 v[72:73], v[74:75], off offset:1024 sc1
	v_cvt_pk_bf16_f32 v74, v40, v41
	v_cvt_pk_bf16_f32 v75, v42, v43
	global_store_dwordx2 v[72:73], v[74:75], off offset:1536 sc1
; __device__ __forceinline__ unsigned cvt_pk_bf16(float lo, float hi) { f32x2_t v = {lo, hi}; bf16x2_t b = __builtin_convertvector(v, bf16x2_t); return __builtin_bit_cast(unsigned, b); }
; template <bool HB, bool FINAL>
; __device__ __forceinline__ void norm_rows(const void* src, const bf16* y, float ys, bf16* hdst, const float* gain, bf16* xn, float* fout, float* fstage, int gw, int NGW, int lane) {
;     ...
;         for (int o = 1; o < 64; o <<= 1) { s[0] += __shfl_xor(s[0], o); s[1] += __shfl_xor(s[1], o); }
; #pragma unroll
;         for (int r = 0; r < 2; ++r) { const int m = m0 + r * NGW; const float rstd = rsqrtf(s[r] * (1.f / D) + EPS);
;             if (!FINAL && hdst) { u32x2* hr = (u32x2*)(hdst + (size_t)m * D) + lane;
; #pragma unroll
;                 for (int j = 0; j < 4; ++j) { u32x2 w; w.x = cvt_pk_bf16(v[r][j].x, v[r][j].y); w.y = cvt_pk_bf16(v[r][j].z, v[r][j].w); hr[64 * j] = w; } }
;             if (FINAL) { f32x4* o = (f32x4*)((m >= T / 2 ? fout : fstage) + (size_t)m * D) + lane;
; #pragma unroll
;                 for (int j = 0; j < 4; ++j) o[64 * j] = v[r][j] * rstd * gv[j];
;             } else { u32x2* o = (u32x2*)(xn + (size_t)m * D) + lane;
; #pragma unroll
;                 for (int j = 0; j < 4; ++j) { const f32x4 q = v[r][j] * rstd * gv[j]; u32x2 w; w.x = cvt_pk_bf16(q.x, q.y); w.y = cvt_pk_bf16(q.z, q.w); o[64 * j] = w; } } }
.LBB0_257:
	s_waitcnt lgkmcnt(1)
	v_add_f32_e32 v69, v69, v70
	v_fmamk_f32 v69, v69, 0x3a800000, v142
	v_mul_f32_e32 v70, 0x4b800000, v69
	v_cmp_gt_f32_e32 vcc, s72, v69
	s_nop 1
	v_cndmask_b32_e32 v69, v69, v70, vcc
	v_rsq_f32_e32 v69, v69
	v_lshl_add_u64 v[70:71], v[22:23], 0, s[16:17]
	v_mul_f32_e32 v72, 0x45800000, v69
	v_cndmask_b32_e32 v72, v69, v72, vcc
	v_pk_mul_f32 v[26:27], v[26:27], v[72:73] op_sel_hi:[1,0]
	v_pk_mul_f32 v[28:29], v[28:29], v[72:73] op_sel_hi:[1,0]
	v_pk_mul_f32 v[26:27], v[2:3], v[26:27]
	v_pk_mul_f32 v[28:29], v[4:5], v[28:29]
	v_cvt_pk_bf16_f32 v26, v26, v27
	v_cvt_pk_bf16_f32 v27, v28, v29
	global_store_dwordx2 v[70:71], v[26:27], off sc1
	v_pk_mul_f32 v[26:27], v[30:31], v[72:73] op_sel_hi:[1,0]
	v_pk_mul_f32 v[28:29], v[32:33], v[72:73] op_sel_hi:[1,0]
	v_pk_mul_f32 v[26:27], v[6:7], v[26:27]
	v_pk_mul_f32 v[28:29], v[8:9], v[28:29]
	v_cvt_pk_bf16_f32 v26, v26, v27
	v_cvt_pk_bf16_f32 v27, v28, v29
	global_store_dwordx2 v[70:71], v[26:27], off offset:512 sc1
	v_pk_mul_f32 v[26:27], v[36:37], v[72:73] op_sel_hi:[1,0]
	v_pk_mul_f32 v[28:29], v[38:39], v[72:73] op_sel_hi:[1,0]
	v_pk_mul_f32 v[26:27], v[10:11], v[26:27]
	v_pk_mul_f32 v[28:29], v[12:13], v[28:29]
	v_cvt_pk_bf16_f32 v26, v26, v27
	v_cvt_pk_bf16_f32 v27, v28, v29
	global_store_dwordx2 v[70:71], v[26:27], off offset:1024 sc1
	v_pk_mul_f32 v[26:27], v[40:41], v[72:73] op_sel_hi:[1,0]
	v_pk_mul_f32 v[28:29], v[42:43], v[72:73] op_sel_hi:[1,0]
	v_pk_mul_f32 v[26:27], v[14:15], v[26:27]
	v_pk_mul_f32 v[28:29], v[16:17], v[28:29]
	v_cvt_pk_bf16_f32 v26, v26, v27
	v_cvt_pk_bf16_f32 v27, v28, v29
	s_and_b64 vcc, exec, s[6:7]
	global_store_dwordx2 v[70:71], v[26:27], off offset:1536 sc1
	s_cbranch_vccnz .LBB0_254
	v_lshl_add_u64 v[26:27], v[24:25], 0, s[14:15]
	v_cvt_pk_bf16_f32 v28, v60, v61
	v_cvt_pk_bf16_f32 v29, v54, v55
	global_store_dwordx2 v[26:27], v[28:29], off sc1
	v_cvt_pk_bf16_f32 v28, v58, v59
	v_cvt_pk_bf16_f32 v29, v50, v51
	global_store_dwordx2 v[26:27], v[28:29], off offset:512 sc1
	v_cvt_pk_bf16_f32 v28, v56, v57
	v_cvt_pk_bf16_f32 v29, v46, v47
	global_store_dwordx2 v[26:27], v[28:29], off offset:1024 sc1
	v_cvt_pk_bf16_f32 v28, v52, v53
	v_cvt_pk_bf16_f32 v29, v44, v45
	global_store_dwordx2 v[26:27], v[28:29], off offset:1536 sc1
	s_branch .LBB0_254
